# OUT and OUT2 split-K extras moved onto on-time workgroups (flipped index 64..111)
# speedup vs baseline: 1.0008x; 1.0008x over previous
.LBB0_655:
	s_movk_i32 s8, 0x100
	v_mov_b32_e32 v8, v153
	s_sub_u32 s100, s101, 64
	s_and_b32 s100, s100, 0xff
	s_cmp_lt_i32 s100, 48
	s_cselect_b64 s[0:1], -1, 0
	s_cmp_gt_i32 s100, 47
	v_readfirstlane_b32 s9, v8
	s_cbranch_scc1 .LBB0_657
	s_ashr_i32 s6, s100, 31
	s_lshr_b32 s6, s6, 28
	s_add_i32 s6, s100, s6
	s_ashr_i32 s7, s6, 4
	s_and_b32 s6, s6, -16
	s_add_i32 s14, s7, 64
	s_sub_i32 s16, s100, s6

.LBB0_681:
	s_sub_u32 s100, s101, 64
	s_and_b32 s100, s100, 0xff
	s_add_i32 s49, s49, 1
	s_mul_i32 s6, s49, s26
	s_add_i32 s6, s6, s100
	s_cmp_lt_i32 s6, 48
	s_cselect_b64 s[84:85], -1, 0
	s_cmp_gt_i32 s6, 47
	s_cbranch_scc1 .LBB0_683
	s_ashr_i32 s7, s6, 31
	s_lshr_b32 s7, s7, 28
	s_add_i32 s7, s6, s7
	s_ashr_i32 s8, s7, 4
	s_and_b32 s7, s7, -16
	s_add_i32 s72, s8, 64
	s_sub_i32 s50, s6, s7

.LBB0_1899:
	v_readlane_b32 s6, v255, 0
	s_movk_i32 s8, 0x100
	v_mov_b32_e32 v8, v153
	v_readlane_b32 s7, v255, 1
	s_and_b64 vcc, exec, s[6:7]
	v_readfirstlane_b32 s9, v8
	s_cbranch_vccnz .LBB0_1901
	s_sub_u32 s100, s101, 64
	s_and_b32 s100, s100, 0xff
	s_ashr_i32 s0, s100, 31
	s_lshr_b32 s0, s0, 28
	s_add_i32 s0, s100, s0
	s_ashr_i32 s1, s0, 4
	s_and_b32 s0, s0, -16
	s_add_i32 s14, s1, 64
	s_sub_i32 s12, s100, s0

.LBB0_1925:
	s_sub_u32 s100, s101, 64
	s_and_b32 s100, s100, 0xff
	s_add_i32 s41, s41, 1
	s_mul_i32 s6, s41, s26
	s_add_i32 s6, s6, s100
	s_cmp_lt_i32 s6, 48
	s_cselect_b64 s[74:75], -1, 0
	s_cmp_gt_i32 s6, 47
	s_cbranch_scc1 .LBB0_1927
	s_ashr_i32 s7, s6, 31
	s_lshr_b32 s7, s7, 28
	s_add_i32 s7, s6, s7
	s_ashr_i32 s8, s7, 4
	s_and_b32 s7, s7, -16
	s_add_i32 s62, s8, 64
	s_sub_i32 s48, s6, s7
